# baseline (speedup 1.0000x reference)
; #define STAGE(P, BASE, br, kt) do { const char* _gb = (const char*)(BASE) + ((size_t)(br) * K + (size_t)(kt) * BK) * 2; \
;     __builtin_amdgcn_global_load_lds((const unsigned*)(_gb + loff0), (unsigned*)((char*)(P) + tid * 16), 16, 0, 0); \
;     __builtin_amdgcn_global_load_lds((const unsigned*)(_gb + (size_t)K * 128 + loff0), (unsigned*)((char*)(P) + tid * 16 + 8192), 16, 0, 0); } while (0)
; #define WAIT_V(n) asm volatile("s_waitcnt vmcnt(" #n ")" ::: "memory")
; #define BAR __builtin_amdgcn_s_barrier()
; template <int EPI> ...
;     ...
;   f32x4 acc[2][2][4][2] = {};
;   bf16x8 At[4][2], B0[2][2], B1[2][2];
;   int nt = K / BK;
;   const int aoff0 = lds_byte(wr * 64 + fr, fq * 8), aoff1 = lds_byte(wr * 64 + fr, 32 + fq * 8);
;   const int brw = wc * 32 + (fr >> 2) * 8 + (fr & 3);
;   const int boff0 = lds_byte(brw, fq * 8), boff1 = lds_byte(brw, 32 + fq * 8);
;   unsigned loff0;
;   { int _r, _c; stage_rc(tid * 16, _r, _c); loff0 = (unsigned)(_r * K + _c) * 2u; }
;   STAGE(SB(0, 0), Bt, bcol, 0); STAGE(SA(0, 0), A, brow, 0);
;   STAGE(SB(0, 1), Bt, bcol + HALF, 0); STAGE(SA(0, 1), A, brow + HALF, 0);
;   if (wr == 1) BAR;
;   WAIT_V(4); BAR;
;   STAGE(SB(1, 0), Bt, bcol, 1); STAGE(SA(1, 0), A, brow, 1); STAGE(SB(1, 1), Bt, bcol + HALF, 1);
;   WAIT_V(6); BAR;
; template <int EPI>
; __device__ __forceinline__ void gemm_phase(const u16* A, const u16* Bt, int M, int N, int K, u16* out, int ldo,
;                                            const float* aux, int bid, int nblk, int wv) {
;     ...
;   for (int base = 0; base < ntile; base += nblk) {
;     int wgid;
;     if (base + nblk <= ntile && (nblk & 7) == 0) wgid = base + (bid & 7) * (nblk >> 3) + (bid >> 3);
;     else wgid = base + bid;
;     if (wgid >= ntile) break;
;     int nig = WGM * nN, gid = wgid / nig, fm = gid * WGM, gsz = min(nM - fm, WGM);
;     int pm = fm + ((wgid % nig) % gsz), pn = (wgid % nig) / gsz;
;     int brow = pm * BM, bcol = pn * BM;
.LBB0_273:
	s_mov_b32 s68, s74
	s_add_i32 s74, s74, s33
	s_cmpk_lt_i32 s74, 0x1601
	s_cselect_b64 s[66:67], -1, 0
	s_and_b64 s[66:67], s[44:45], s[66:67]
	s_and_b64 s[66:67], s[66:67], exec
	s_cselect_b32 s66, s86, s91
	s_add_i32 s68, s66, s68
	s_cmpk_gt_i32 s68, 0x15ff
	s_mov_b64 s[66:67], -1
	s_cbranch_scc1 .LBB0_272
	s_mul_hi_i32 s66, s68, 0x2e8ba2e9
	s_lshr_b32 s67, s66, 31
	s_ashr_i32 s66, s66, 6
	s_add_i32 s66, s66, s67
	s_mul_i32 s67, s66, 0x160
	s_sub_i32 s67, s68, s67
	s_sext_i32_i16 s68, s67
	s_bfe_u32 s68, s68, 0x3001c
	s_add_i32 s68, s67, s68
	s_sext_i32_i16 s69, s68
	s_and_b32 s68, s68, 0xfff8
	s_sub_i32 s67, s67, s68
	s_ashr_i32 s76, s69, 3
	s_sext_i32_i16 s67, s67
	s_lshl_b32 s72, s76, 8
	s_lshl_b32 s66, s66, 11
	s_lshl_b32 s67, s67, 8
	s_ashr_i32 s73, s72, 31
	s_add_i32 s66, s67, s66
	s_lshl_b64 s[68:69], s[72:73], 12
	s_add_u32 s68, s6, s68
	s_addc_u32 s69, s7, s69
	v_readfirstlane_b32 s67, v136
	v_lshl_add_u64 v[0:1], s[68:69], 0, v[128:129]
	s_mov_b32 m0, s67
	v_readfirstlane_b32 s67, v137
	global_load_lds_dwordx4 v[0:1], off
	s_mov_b32 m0, s67
	s_ashr_i32 s67, s66, 31
	s_lshl_b64 s[70:71], s[66:67], 12
	s_add_u32 s78, s14, s70
	s_addc_u32 s79, s43, s71
	s_bitset1_b32 s72, 7
	s_ashr_i32 s73, s72, 31
	v_lshl_add_u64 v[2:3], v[0:1], 0, s[10:11]
	v_readfirstlane_b32 s67, v138
	s_lshl_b64 s[72:73], s[72:73], 12
	global_load_lds_dwordx4 v[2:3], off
	v_lshl_add_u64 v[2:3], s[78:79], 0, v[128:129]
	s_mov_b32 m0, s67
	v_readfirstlane_b32 s67, v139
	s_add_u32 s72, s6, s72
	global_load_lds_dwordx4 v[2:3], off
	v_lshl_add_u64 v[4:5], v[2:3], 0, s[10:11]
	s_mov_b32 m0, s67
	s_addc_u32 s73, s7, s73
	global_load_lds_dwordx4 v[4:5], off
	v_lshl_add_u64 v[4:5], s[72:73], 0, v[128:129]
	s_or_b32 s72, s66, 0x80
	s_ashr_i32 s73, s72, 31
	v_readfirstlane_b32 s67, v140
	s_lshl_b64 s[72:73], s[72:73], 12
	s_mov_b32 m0, s67
	v_readfirstlane_b32 s67, v141
	s_add_u32 s72, s14, s72
	global_load_lds_dwordx4 v[4:5], off
	v_lshl_add_u64 v[6:7], v[4:5], 0, s[10:11]
	s_mov_b32 m0, s67
	s_addc_u32 s73, s43, s73
	v_readfirstlane_b32 s67, v142
	global_load_lds_dwordx4 v[6:7], off
	v_lshl_add_u64 v[132:133], s[72:73], 0, v[128:129]
	s_mov_b32 m0, s67
	v_readfirstlane_b32 s67, v143
	global_load_lds_dwordx4 v[132:133], off
	v_lshl_add_u64 v[6:7], v[132:133], 0, s[10:11]
	s_mov_b32 m0, s67
	s_nop 0
	global_load_lds_dwordx4 v[6:7], off
	v_mov_b32_e32 v8, 0
	v_mov_b32_e32 v9, 0
	v_mov_b32_e32 v10, 0
	v_mov_b32_e32 v11, 0
	v_mov_b32_e32 v12, 0
	v_mov_b32_e32 v13, 0
	v_mov_b32_e32 v14, 0
	v_mov_b32_e32 v15, 0
	v_mov_b32_e32 v16, 0
	v_mov_b32_e32 v17, 0
	v_mov_b32_e32 v18, 0
	v_mov_b32_e32 v19, 0
	v_mov_b32_e32 v20, 0
	v_mov_b32_e32 v21, 0
	v_mov_b32_e32 v22, 0
	v_mov_b32_e32 v23, 0
	v_mov_b32_e32 v24, 0
	v_mov_b32_e32 v25, 0
	v_mov_b32_e32 v26, 0
	v_mov_b32_e32 v27, 0
	v_mov_b32_e32 v28, 0
	v_mov_b32_e32 v29, 0
	v_mov_b32_e32 v30, 0
	v_mov_b32_e32 v31, 0
	v_mov_b32_e32 v32, 0
	v_mov_b32_e32 v33, 0
	v_mov_b32_e32 v34, 0
	v_mov_b32_e32 v35, 0
	v_mov_b32_e32 v36, 0
	v_mov_b32_e32 v37, 0
	v_mov_b32_e32 v38, 0
	v_mov_b32_e32 v39, 0
	v_mov_b32_e32 v40, 0
	v_mov_b32_e32 v41, 0
	v_mov_b32_e32 v42, 0
	v_mov_b32_e32 v43, 0
	v_mov_b32_e32 v44, 0
	v_mov_b32_e32 v45, 0
	v_mov_b32_e32 v46, 0
	v_mov_b32_e32 v47, 0
	v_mov_b32_e32 v48, 0
	v_mov_b32_e32 v49, 0
	v_mov_b32_e32 v50, 0
	v_mov_b32_e32 v51, 0
	v_mov_b32_e32 v52, 0
	v_mov_b32_e32 v53, 0
	v_mov_b32_e32 v54, 0
	v_mov_b32_e32 v55, 0
	v_mov_b32_e32 v56, 0
	v_mov_b32_e32 v57, 0
	v_mov_b32_e32 v58, 0
	v_mov_b32_e32 v59, 0
	v_mov_b32_e32 v60, 0
	v_mov_b32_e32 v61, 0
	v_mov_b32_e32 v62, 0
	v_mov_b32_e32 v63, 0
	v_mov_b32_e32 v64, 0
	v_mov_b32_e32 v65, 0
	v_mov_b32_e32 v66, 0
	v_mov_b32_e32 v67, 0
	v_mov_b32_e32 v68, 0
	v_mov_b32_e32 v69, 0
	v_mov_b32_e32 v70, 0
	v_mov_b32_e32 v71, 0
	v_mov_b32_e32 v72, 0
	v_mov_b32_e32 v73, 0
	v_mov_b32_e32 v74, 0
	v_mov_b32_e32 v75, 0
	v_mov_b32_e32 v76, 0
	v_mov_b32_e32 v77, 0
	v_mov_b32_e32 v78, 0
	v_mov_b32_e32 v79, 0
	v_mov_b32_e32 v80, 0
	v_mov_b32_e32 v81, 0
	v_mov_b32_e32 v82, 0
	v_mov_b32_e32 v83, 0
	v_mov_b32_e32 v84, 0
	v_mov_b32_e32 v85, 0
	v_mov_b32_e32 v86, 0
	v_mov_b32_e32 v87, 0
	v_mov_b32_e32 v88, 0
	v_mov_b32_e32 v89, 0
	v_mov_b32_e32 v90, 0
	v_mov_b32_e32 v91, 0
	v_mov_b32_e32 v92, 0
	v_mov_b32_e32 v93, 0
	v_mov_b32_e32 v94, 0
	v_mov_b32_e32 v95, 0
	v_mov_b32_e32 v96, 0
	v_mov_b32_e32 v97, 0
	v_mov_b32_e32 v98, 0
	v_mov_b32_e32 v99, 0
	v_mov_b32_e32 v100, 0
	v_mov_b32_e32 v101, 0
	v_mov_b32_e32 v102, 0
	v_mov_b32_e32 v103, 0
	v_mov_b32_e32 v104, 0
	v_mov_b32_e32 v105, 0
	v_mov_b32_e32 v106, 0
	v_mov_b32_e32 v107, 0
	v_mov_b32_e32 v108, 0
	v_mov_b32_e32 v109, 0
	v_mov_b32_e32 v110, 0
	v_mov_b32_e32 v111, 0
	v_mov_b32_e32 v112, 0
	v_mov_b32_e32 v113, 0
	v_mov_b32_e32 v114, 0
	v_mov_b32_e32 v115, 0
	v_mov_b32_e32 v116, 0
	v_mov_b32_e32 v117, 0
	v_mov_b32_e32 v118, 0
	v_mov_b32_e32 v119, 0
	v_mov_b32_e32 v120, 0
	v_mov_b32_e32 v121, 0
	v_mov_b32_e32 v122, 0
	v_mov_b32_e32 v123, 0
	v_mov_b32_e32 v124, 0
	v_mov_b32_e32 v125, 0
	v_mov_b32_e32 v126, 0
	v_mov_b32_e32 v127, 0
	v_readfirstlane_b32 s67, v144
	v_lshl_add_u64 v[6:7], v[0:1], 0, s[12:13]
	s_mov_b32 m0, s67
	v_readfirstlane_b32 s67, v145
	global_load_lds_dwordx4 v[6:7], off
	v_lshl_add_u64 v[0:1], v[0:1], 0, s[16:17]
	s_mov_b32 m0, s67
	v_readfirstlane_b32 s67, v146
	global_load_lds_dwordx4 v[0:1], off
	v_lshl_add_u64 v[0:1], v[2:3], 0, s[12:13]
	s_mov_b32 m0, s67
	v_readfirstlane_b32 s67, v147
	global_load_lds_dwordx4 v[0:1], off
	v_lshl_add_u64 v[0:1], v[2:3], 0, s[16:17]
	s_mov_b32 m0, s67
	v_readfirstlane_b32 s67, v148
	global_load_lds_dwordx4 v[0:1], off
	v_lshl_add_u64 v[0:1], v[4:5], 0, s[12:13]
	s_mov_b32 m0, s67
	v_readfirstlane_b32 s67, v149
	global_load_lds_dwordx4 v[0:1], off
	v_lshl_add_u64 v[0:1], v[4:5], 0, s[16:17]
	s_mov_b32 m0, s67
	s_nop 0
	global_load_lds_dwordx4 v[0:1], off
	s_and_saveexec_b64 s[72:73], s[4:5]
	s_cbranch_execz .LBB0_276
	s_barrier
.LBB0_276:
	s_or_b64 exec, exec, s[72:73]
	s_waitcnt vmcnt(8)
	s_barrier
	s_add_u32 s70, s6, s70
	v_mov_b32_e32 v0, 0
	s_addc_u32 s71, s7, s71
	s_mov_b32 s67, -2
	v_mov_b32_e32 v1, v0
	v_mov_b32_e32 v2, v0
	v_mov_b32_e32 v3, v0
	v_mov_b32_e32 v4, v0
	v_mov_b32_e32 v5, v0
	v_mov_b32_e32 v6, v0
	v_mov_b32_e32 v7, v0
	s_waitcnt vmcnt(6)
	s_sub_u32 s98, s68, 0x100
	s_subb_u32 s99, s69, 0
	v_lshl_add_u64 v[228:229], s[98:99], 0, v[130:131]
	s_barrier

; #define STAGE(P, BASE, br, kt) do { const char* _gb = (const char*)(BASE) + ((size_t)(br) * K + (size_t)(kt) * BK) * 2; \
;     __builtin_amdgcn_global_load_lds((const unsigned*)(_gb + loff0), (unsigned*)((char*)(P) + tid * 16), 16, 0, 0); \
;     __builtin_amdgcn_global_load_lds((const unsigned*)(_gb + (size_t)K * 128 + loff0), (unsigned*)((char*)(P) + tid * 16 + 8192), 16, 0, 0); } while (0)
; #define WAIT_V(n) asm volatile("s_waitcnt vmcnt(" #n ")" ::: "memory")
; #define BAR __builtin_amdgcn_s_barrier()
; template <int EPI> ...
;     ...
;   f32x4 acc[2][2][4][2] = {};
;   bf16x8 At[4][2], B0[2][2], B1[2][2];
;   int nt = K / BK;
;   const int aoff0 = lds_byte(wr * 64 + fr, fq * 8), aoff1 = lds_byte(wr * 64 + fr, 32 + fq * 8);
;   const int brw = wc * 32 + (fr >> 2) * 8 + (fr & 3);
;   const int boff0 = lds_byte(brw, fq * 8), boff1 = lds_byte(brw, 32 + fq * 8);
;   unsigned loff0;
;   { int _r, _c; stage_rc(tid * 16, _r, _c); loff0 = (unsigned)(_r * K + _c) * 2u; }
;   STAGE(SB(0, 0), Bt, bcol, 0); STAGE(SA(0, 0), A, brow, 0);
;   STAGE(SB(0, 1), Bt, bcol + HALF, 0); STAGE(SA(0, 1), A, brow + HALF, 0);
;   if (wr == 1) BAR;
;   WAIT_V(4); BAR;
;   STAGE(SB(1, 0), Bt, bcol, 1); STAGE(SA(1, 0), A, brow, 1); STAGE(SB(1, 1), Bt, bcol + HALF, 1);
;   WAIT_V(6); BAR;
; template <int EPI>
; __device__ __forceinline__ void gemm_phase(const u16* A, const u16* Bt, int M, int N, int K, u16* out, int ldo,
;                                            const float* aux, int bid, int nblk, int wv) {
;     ...
;   for (int base = 0; base < ntile; base += nblk) {
;     int wgid;
;     if (base + nblk <= ntile && (nblk & 7) == 0) wgid = base + (bid & 7) * (nblk >> 3) + (bid >> 3);
;     else wgid = base + bid;
;     if (wgid >= ntile) break;
;     int nig = WGM * nN, gid = wgid / nig, fm = gid * WGM, gsz = min(nM - fm, WGM);
;     int pm = fm + ((wgid % nig) % gsz), pn = (wgid % nig) / gsz;
;     int brow = pm * BM, bcol = pn * BM;
.LBB0_320:
	s_mov_b32 s62, s72
	s_add_i32 s72, s72, s33
	s_cmpk_lt_i32 s72, 0x401
	s_cselect_b64 s[60:61], -1, 0
	s_and_b64 s[60:61], s[44:45], s[60:61]
	s_and_b64 s[60:61], s[60:61], exec
	s_cselect_b32 s60, s86, s91
	s_add_i32 s62, s60, s62
	s_cmpk_gt_i32 s62, 0x3ff
	s_mov_b64 s[60:61], -1
	s_cbranch_scc1 .LBB0_319
	s_sub_i32 s62, 0x3ff, s62
	s_ashr_i32 s60, s62, 31
	s_lshr_b32 s60, s60, 26
	s_add_i32 s60, s62, s60
	s_and_b32 s61, s60, 0xffc0
	s_sub_i32 s61, s62, s61
	s_bfe_i32 s62, s61, 0x80000
	s_bfe_u32 s62, s62, 0x3000c
	s_add_i32 s62, s61, s62
	s_bfe_i32 s63, s62, 0x80000
	s_and_b32 s62, s62, 0xf8
	s_sub_i32 s61, s61, s62
	s_sext_i32_i16 s63, s63
	s_sext_i32_i8 s61, s61
	s_lshl_b32 s60, s60, 5
	s_ashr_i32 s64, s63, 3
	s_and_b32 s60, s60, 0xfffff800
	s_lshl_b32 s73, s61, 8
	s_add_i32 s73, s73, s60
	s_lshl_b32 s60, s64, 8
	s_mul_i32 s66, s64, 0x2c0000
	s_mul_hi_i32 s67, s60, 0x2c00
	s_add_u32 s62, s68, s66
	s_addc_u32 s63, s69, s67
	v_readfirstlane_b32 s61, v135
	s_mul_i32 s77, s73, 0x2c00
	v_lshl_add_u64 v[0:1], s[62:63], 0, v[128:129]
	s_mov_b32 m0, s61
	v_readfirstlane_b32 s61, v136
	s_mul_hi_i32 s76, s73, 0x2c00
	s_add_u32 s62, s14, s77
	global_load_lds_dwordx4 v[0:1], off
	v_lshl_add_u64 v[2:3], v[0:1], 0, s[8:9]
	s_mov_b32 m0, s61
	s_addc_u32 s63, s43, s76
	global_load_lds_dwordx4 v[2:3], off
	v_lshl_add_u64 v[2:3], s[62:63], 0, v[128:129]
	s_mul_i32 s62, s64, 0x160000
	v_readfirstlane_b32 s61, v137
	s_ashr_i32 s63, s62, 31
	s_mov_b32 m0, s61
	v_readfirstlane_b32 s61, v138
	s_lshl_b64 s[62:63], s[62:63], 1
	global_load_lds_dwordx4 v[2:3], off
	s_mov_b32 m0, s61
	s_add_u32 s61, s68, s62
	s_addc_u32 s65, s69, s63
	s_add_u32 s64, s61, 0x160000
	v_lshl_add_u64 v[4:5], v[2:3], 0, s[8:9]
	s_addc_u32 s65, s65, 0
	v_readfirstlane_b32 s61, v139
	global_load_lds_dwordx4 v[4:5], off
	v_lshl_add_u64 v[4:5], s[64:65], 0, v[128:129]
	s_mov_b32 m0, s61
	v_readfirstlane_b32 s61, v140
	global_load_lds_dwordx4 v[4:5], off
	s_mov_b32 m0, s61
	s_or_b32 s61, s73, 0x80
	s_mul_i32 s75, s61, 0x2c00
	s_mul_hi_i32 s74, s61, 0x2c00
	s_add_u32 s64, s14, s75
	v_lshl_add_u64 v[6:7], v[4:5], 0, s[8:9]
	s_addc_u32 s65, s43, s74
	v_readfirstlane_b32 s61, v141
	global_load_lds_dwordx4 v[6:7], off
	v_lshl_add_u64 v[6:7], s[64:65], 0, v[128:129]
	s_mov_b32 m0, s61
	v_readfirstlane_b32 s61, v142
	global_load_lds_dwordx4 v[6:7], off
	v_lshl_add_u64 v[6:7], v[6:7], 0, s[8:9]
	s_mov_b32 m0, s61
	s_nop 0
	global_load_lds_dwordx4 v[6:7], off
	v_mov_b32_e32 v8, 0
	v_mov_b32_e32 v9, 0
	v_mov_b32_e32 v10, 0
	v_mov_b32_e32 v11, 0
	v_mov_b32_e32 v12, 0
	v_mov_b32_e32 v13, 0
	v_mov_b32_e32 v14, 0
	v_mov_b32_e32 v15, 0
	v_mov_b32_e32 v16, 0
	v_mov_b32_e32 v17, 0
	v_mov_b32_e32 v18, 0
	v_mov_b32_e32 v19, 0
	v_mov_b32_e32 v20, 0
	v_mov_b32_e32 v21, 0
	v_mov_b32_e32 v22, 0
	v_mov_b32_e32 v23, 0
	v_mov_b32_e32 v24, 0
	v_mov_b32_e32 v25, 0
	v_mov_b32_e32 v26, 0
	v_mov_b32_e32 v27, 0
	v_mov_b32_e32 v28, 0
	v_mov_b32_e32 v29, 0
	v_mov_b32_e32 v30, 0
	v_mov_b32_e32 v31, 0
	v_mov_b32_e32 v32, 0
	v_mov_b32_e32 v33, 0
	v_mov_b32_e32 v34, 0
	v_mov_b32_e32 v35, 0
	v_mov_b32_e32 v36, 0
	v_mov_b32_e32 v37, 0
	v_mov_b32_e32 v38, 0
	v_mov_b32_e32 v39, 0
	v_mov_b32_e32 v40, 0
	v_mov_b32_e32 v41, 0
	v_mov_b32_e32 v42, 0
	v_mov_b32_e32 v43, 0
	v_mov_b32_e32 v44, 0
	v_mov_b32_e32 v45, 0
	v_mov_b32_e32 v46, 0
	v_mov_b32_e32 v47, 0
	v_mov_b32_e32 v48, 0
	v_mov_b32_e32 v49, 0
	v_mov_b32_e32 v50, 0
	v_mov_b32_e32 v51, 0
	v_mov_b32_e32 v52, 0
	v_mov_b32_e32 v53, 0
	v_mov_b32_e32 v54, 0
	v_mov_b32_e32 v55, 0
	v_mov_b32_e32 v56, 0
	v_mov_b32_e32 v57, 0
	v_mov_b32_e32 v58, 0
	v_mov_b32_e32 v59, 0
	v_mov_b32_e32 v60, 0
	v_mov_b32_e32 v61, 0
	v_mov_b32_e32 v62, 0
	v_mov_b32_e32 v63, 0
	v_mov_b32_e32 v64, 0
	v_mov_b32_e32 v65, 0
	v_mov_b32_e32 v66, 0
	v_mov_b32_e32 v67, 0
	v_mov_b32_e32 v68, 0
	v_mov_b32_e32 v69, 0
	v_mov_b32_e32 v70, 0
	v_mov_b32_e32 v71, 0
	v_mov_b32_e32 v72, 0
	v_mov_b32_e32 v73, 0
	v_mov_b32_e32 v74, 0
	v_mov_b32_e32 v75, 0
	v_mov_b32_e32 v76, 0
	v_mov_b32_e32 v77, 0
	v_mov_b32_e32 v78, 0
	v_mov_b32_e32 v79, 0
	v_mov_b32_e32 v80, 0
	v_mov_b32_e32 v81, 0
	v_mov_b32_e32 v82, 0
	v_mov_b32_e32 v83, 0
	v_mov_b32_e32 v84, 0
	v_mov_b32_e32 v85, 0
	v_mov_b32_e32 v86, 0
	v_mov_b32_e32 v87, 0
	v_mov_b32_e32 v88, 0
	v_mov_b32_e32 v89, 0
	v_mov_b32_e32 v90, 0
	v_mov_b32_e32 v91, 0
	v_mov_b32_e32 v92, 0
	v_mov_b32_e32 v93, 0
	v_mov_b32_e32 v94, 0
	v_mov_b32_e32 v95, 0
	v_mov_b32_e32 v96, 0
	v_mov_b32_e32 v97, 0
	v_mov_b32_e32 v98, 0
	v_mov_b32_e32 v99, 0
	v_mov_b32_e32 v100, 0
	v_mov_b32_e32 v101, 0
	v_mov_b32_e32 v102, 0
	v_mov_b32_e32 v103, 0
	v_mov_b32_e32 v104, 0
	v_mov_b32_e32 v105, 0
	v_mov_b32_e32 v106, 0
	v_mov_b32_e32 v107, 0
	v_mov_b32_e32 v108, 0
	v_mov_b32_e32 v109, 0
	v_mov_b32_e32 v110, 0
	v_mov_b32_e32 v111, 0
	v_mov_b32_e32 v112, 0
	v_mov_b32_e32 v113, 0
	v_mov_b32_e32 v114, 0
	v_mov_b32_e32 v115, 0
	v_mov_b32_e32 v116, 0
	v_mov_b32_e32 v117, 0
	v_mov_b32_e32 v118, 0
	v_mov_b32_e32 v119, 0
	v_mov_b32_e32 v120, 0
	v_mov_b32_e32 v121, 0
	v_mov_b32_e32 v122, 0
	v_mov_b32_e32 v123, 0
	v_mov_b32_e32 v124, 0
	v_mov_b32_e32 v125, 0
	v_mov_b32_e32 v126, 0
	v_mov_b32_e32 v127, 0
	v_readfirstlane_b32 s64, v143
	v_lshl_add_u64 v[6:7], v[0:1], 0, s[10:11]
	s_mov_b32 m0, s64
	v_readfirstlane_b32 s64, v144
	global_load_lds_dwordx4 v[6:7], off
	v_lshl_add_u64 v[0:1], v[0:1], 0, s[12:13]
	s_mov_b32 m0, s64
	v_readfirstlane_b32 s64, v145
	global_load_lds_dwordx4 v[0:1], off
	v_lshl_add_u64 v[0:1], v[2:3], 0, s[10:11]
	s_mov_b32 m0, s64
	v_readfirstlane_b32 s64, v146
	global_load_lds_dwordx4 v[0:1], off
	v_lshl_add_u64 v[0:1], v[2:3], 0, s[12:13]
	s_mov_b32 m0, s64
	v_readfirstlane_b32 s64, v147
	global_load_lds_dwordx4 v[0:1], off
	v_lshl_add_u64 v[0:1], v[4:5], 0, s[10:11]
	s_mov_b32 m0, s64
	v_readfirstlane_b32 s64, v148
	global_load_lds_dwordx4 v[0:1], off
	v_lshl_add_u64 v[0:1], v[4:5], 0, s[12:13]
	s_mov_b32 m0, s64
	s_nop 0
	global_load_lds_dwordx4 v[0:1], off
	s_and_saveexec_b64 s[64:65], s[4:5]
	s_cbranch_execz .LBB0_323
	s_barrier
.LBB0_323:
	s_or_b64 exec, exec, s[64:65]
	s_waitcnt vmcnt(8)
	s_barrier
	s_ashr_i32 s61, s60, 31
	s_add_u32 s62, s6, s62
	s_addc_u32 s63, s7, s63
	s_add_u32 s64, s6, s77
	s_addc_u32 s65, s7, s76
	s_add_u32 s66, s6, s66
	v_mov_b32_e32 v0, 0
	s_addc_u32 s67, s7, s67
	s_mov_b32 s76, -2
	v_mov_b32_e32 v1, v0
	v_mov_b32_e32 v2, v0
	v_mov_b32_e32 v3, v0
	v_mov_b32_e32 v4, v0
	v_mov_b32_e32 v5, v0
	v_mov_b32_e32 v6, v0
	v_mov_b32_e32 v7, v0
	s_waitcnt vmcnt(6)
	s_sub_u32 s98, s62, 0x100
	s_subb_u32 s99, s63, 0
	v_lshl_add_u64 v[228:229], s[98:99], 0, v[132:133]
	s_barrier

; #define STAGE(P, BASE, br, kt) do { const char* _gb = (const char*)(BASE) + ((size_t)(br) * K + (size_t)(kt) * BK) * 2; \
;     __builtin_amdgcn_global_load_lds((const unsigned*)(_gb + loff0), (unsigned*)((char*)(P) + tid * 16), 16, 0, 0); \
;     __builtin_amdgcn_global_load_lds((const unsigned*)(_gb + (size_t)K * 128 + loff0), (unsigned*)((char*)(P) + tid * 16 + 8192), 16, 0, 0); } while (0)
; #define WAIT_V(n) asm volatile("s_waitcnt vmcnt(" #n ")" ::: "memory")
; #define BAR __builtin_amdgcn_s_barrier()
; template <int EPI> ...
;     ...
;   f32x4 acc[2][2][4][2] = {};
;   bf16x8 At[4][2], B0[2][2], B1[2][2];
;   int nt = K / BK;
;   const int aoff0 = lds_byte(wr * 64 + fr, fq * 8), aoff1 = lds_byte(wr * 64 + fr, 32 + fq * 8);
;   const int brw = wc * 32 + (fr >> 2) * 8 + (fr & 3);
;   const int boff0 = lds_byte(brw, fq * 8), boff1 = lds_byte(brw, 32 + fq * 8);
;   unsigned loff0;
;   { int _r, _c; stage_rc(tid * 16, _r, _c); loff0 = (unsigned)(_r * K + _c) * 2u; }
;   STAGE(SB(0, 0), Bt, bcol, 0); STAGE(SA(0, 0), A, brow, 0);
;   STAGE(SB(0, 1), Bt, bcol + HALF, 0); STAGE(SA(0, 1), A, brow + HALF, 0);
;   if (wr == 1) BAR;
;   WAIT_V(4); BAR;
;   STAGE(SB(1, 0), Bt, bcol, 1); STAGE(SA(1, 0), A, brow, 1); STAGE(SB(1, 1), Bt, bcol + HALF, 1);
;   WAIT_V(6); BAR;
; template <int EPI>
; __device__ __forceinline__ void gemm_phase(const u16* A, const u16* Bt, int M, int N, int K, u16* out, int ldo,
;                                            const float* aux, int bid, int nblk, int wv) {
;     ...
;   for (int base = 0; base < ntile; base += nblk) {
;     int wgid;
;     if (base + nblk <= ntile && (nblk & 7) == 0) wgid = base + (bid & 7) * (nblk >> 3) + (bid >> 3);
;     else wgid = base + bid;
;     if (wgid >= ntile) break;
;     int nig = WGM * nN, gid = wgid / nig, fm = gid * WGM, gsz = min(nM - fm, WGM);
;     int pm = fm + ((wgid % nig) % gsz), pn = (wgid % nig) / gsz;
;     int brow = pm * BM, bcol = pn * BM;
;     gemm_tile<EPI>(A, Bt, K, brow, bcol, out, ldo, EPI == 1 ? pn * HALF : bcol, aux, tid);
.LBB0_407:
	s_mov_b32 s62, s76
	s_add_i32 s76, s76, s33
	s_cmpk_lt_i32 s76, 0xb01
	s_cselect_b64 s[60:61], -1, 0
	s_and_b64 s[60:61], s[44:45], s[60:61]
	s_and_b64 s[60:61], s[60:61], exec
	s_cselect_b32 s60, s86, s91
	s_add_i32 s62, s60, s62
	s_cmpk_gt_i32 s62, 0xaff
	s_mov_b64 s[60:61], -1
	s_cbranch_scc1 .LBB0_406
	s_mul_hi_i32 s60, s62, 0x2e8ba2e9
	s_lshr_b32 s61, s60, 31
	s_ashr_i32 s60, s60, 5
	s_add_i32 s60, s60, s61
	s_mul_i32 s61, s60, 0xb0
	s_sub_i32 s61, s62, s61
	s_sext_i32_i16 s62, s61
	s_bfe_u32 s62, s62, 0x3001c
	s_add_i32 s62, s61, s62
	s_sext_i32_i16 s63, s62
	s_and_b32 s62, s62, 0xfff8
	s_sub_i32 s61, s61, s62
	s_sext_i32_i16 s61, s61
	s_lshl_b32 s60, s60, 11
	s_lshl_b32 s61, s61, 8
	s_add_i32 s60, s61, s60
	s_lshl_b32 s61, s63, 5
	s_and_b32 s62, s61, 0xffffff00
	s_ashr_i32 s63, s62, 31
	s_lshl_b64 s[66:67], s[62:63], 12
	s_add_u32 s64, s72, s66
	s_addc_u32 s65, s73, s67
	v_readfirstlane_b32 s61, v135
	v_lshl_add_u64 v[0:1], s[64:65], 0, v[128:129]
	s_mov_b32 m0, s61
	v_readfirstlane_b32 s61, v136
	global_load_lds_dwordx4 v[0:1], off
	s_mov_b32 m0, s61
	s_ashr_i32 s61, s60, 31
	s_lshl_b64 s[68:69], s[60:61], 12
	s_add_u32 s64, s14, s68
	v_lshl_add_u64 v[2:3], v[0:1], 0, s[8:9]
	s_addc_u32 s65, s43, s69
	global_load_lds_dwordx4 v[2:3], off
	v_lshl_add_u64 v[2:3], s[64:65], 0, v[128:129]
	s_or_b32 s64, s62, 0x80
	s_ashr_i32 s65, s64, 31
	v_readfirstlane_b32 s61, v137
	s_lshl_b64 s[64:65], s[64:65], 12
	s_mov_b32 m0, s61
	v_readfirstlane_b32 s61, v138
	s_add_u32 s64, s72, s64
	global_load_lds_dwordx4 v[2:3], off
	v_lshl_add_u64 v[4:5], v[2:3], 0, s[8:9]
	s_mov_b32 m0, s61
	s_addc_u32 s65, s73, s65
	global_load_lds_dwordx4 v[4:5], off
	v_lshl_add_u64 v[4:5], s[64:65], 0, v[128:129]
	s_or_b32 s64, s60, 0x80
	s_ashr_i32 s65, s64, 31
	v_readfirstlane_b32 s61, v139
	s_lshl_b64 s[64:65], s[64:65], 12
	s_mov_b32 m0, s61
	v_readfirstlane_b32 s61, v140
	s_add_u32 s70, s14, s64
	global_load_lds_dwordx4 v[4:5], off
	v_lshl_add_u64 v[6:7], v[4:5], 0, s[8:9]
	s_mov_b32 m0, s61
	s_addc_u32 s71, s43, s65
	v_readfirstlane_b32 s61, v141
	global_load_lds_dwordx4 v[6:7], off
	v_lshl_add_u64 v[6:7], s[70:71], 0, v[128:129]
	s_mov_b32 m0, s61
	v_readfirstlane_b32 s61, v142
	global_load_lds_dwordx4 v[6:7], off
	v_lshl_add_u64 v[6:7], v[6:7], 0, s[8:9]
	s_mov_b32 m0, s61
	s_nop 0
	global_load_lds_dwordx4 v[6:7], off
	v_mov_b32_e32 v8, 0
	v_mov_b32_e32 v9, 0
	v_mov_b32_e32 v10, 0
	v_mov_b32_e32 v11, 0
	v_mov_b32_e32 v12, 0
	v_mov_b32_e32 v13, 0
	v_mov_b32_e32 v14, 0
	v_mov_b32_e32 v15, 0
	v_mov_b32_e32 v16, 0
	v_mov_b32_e32 v17, 0
	v_mov_b32_e32 v18, 0
	v_mov_b32_e32 v19, 0
	v_mov_b32_e32 v20, 0
	v_mov_b32_e32 v21, 0
	v_mov_b32_e32 v22, 0
	v_mov_b32_e32 v23, 0
	v_mov_b32_e32 v24, 0
	v_mov_b32_e32 v25, 0
	v_mov_b32_e32 v26, 0
	v_mov_b32_e32 v27, 0
	v_mov_b32_e32 v28, 0
	v_mov_b32_e32 v29, 0
	v_mov_b32_e32 v30, 0
	v_mov_b32_e32 v31, 0
	v_mov_b32_e32 v32, 0
	v_mov_b32_e32 v33, 0
	v_mov_b32_e32 v34, 0
	v_mov_b32_e32 v35, 0
	v_mov_b32_e32 v36, 0
	v_mov_b32_e32 v37, 0
	v_mov_b32_e32 v38, 0
	v_mov_b32_e32 v39, 0
	v_mov_b32_e32 v40, 0
	v_mov_b32_e32 v41, 0
	v_mov_b32_e32 v42, 0
	v_mov_b32_e32 v43, 0
	v_mov_b32_e32 v44, 0
	v_mov_b32_e32 v45, 0
	v_mov_b32_e32 v46, 0
	v_mov_b32_e32 v47, 0
	v_mov_b32_e32 v48, 0
	v_mov_b32_e32 v49, 0
	v_mov_b32_e32 v50, 0
	v_mov_b32_e32 v51, 0
	v_mov_b32_e32 v52, 0
	v_mov_b32_e32 v53, 0
	v_mov_b32_e32 v54, 0
	v_mov_b32_e32 v55, 0
	v_mov_b32_e32 v56, 0
	v_mov_b32_e32 v57, 0
	v_mov_b32_e32 v58, 0
	v_mov_b32_e32 v59, 0
	v_mov_b32_e32 v60, 0
	v_mov_b32_e32 v61, 0
	v_mov_b32_e32 v62, 0
	v_mov_b32_e32 v63, 0
	v_mov_b32_e32 v64, 0
	v_mov_b32_e32 v65, 0
	v_mov_b32_e32 v66, 0
	v_mov_b32_e32 v67, 0
	v_mov_b32_e32 v68, 0
	v_mov_b32_e32 v69, 0
	v_mov_b32_e32 v70, 0
	v_mov_b32_e32 v71, 0
	v_mov_b32_e32 v72, 0
	v_mov_b32_e32 v73, 0
	v_mov_b32_e32 v74, 0
	v_mov_b32_e32 v75, 0
	v_mov_b32_e32 v76, 0
	v_mov_b32_e32 v77, 0
	v_mov_b32_e32 v78, 0
	v_mov_b32_e32 v79, 0
	v_mov_b32_e32 v80, 0
	v_mov_b32_e32 v81, 0
	v_mov_b32_e32 v82, 0
	v_mov_b32_e32 v83, 0
	v_mov_b32_e32 v84, 0
	v_mov_b32_e32 v85, 0
	v_mov_b32_e32 v86, 0
	v_mov_b32_e32 v87, 0
	v_mov_b32_e32 v88, 0
	v_mov_b32_e32 v89, 0
	v_mov_b32_e32 v90, 0
	v_mov_b32_e32 v91, 0
	v_mov_b32_e32 v92, 0
	v_mov_b32_e32 v93, 0
	v_mov_b32_e32 v94, 0
	v_mov_b32_e32 v95, 0
	v_mov_b32_e32 v96, 0
	v_mov_b32_e32 v97, 0
	v_mov_b32_e32 v98, 0
	v_mov_b32_e32 v99, 0
	v_mov_b32_e32 v100, 0
	v_mov_b32_e32 v101, 0
	v_mov_b32_e32 v102, 0
	v_mov_b32_e32 v103, 0
	v_mov_b32_e32 v104, 0
	v_mov_b32_e32 v105, 0
	v_mov_b32_e32 v106, 0
	v_mov_b32_e32 v107, 0
	v_mov_b32_e32 v108, 0
	v_mov_b32_e32 v109, 0
	v_mov_b32_e32 v110, 0
	v_mov_b32_e32 v111, 0
	v_mov_b32_e32 v112, 0
	v_mov_b32_e32 v113, 0
	v_mov_b32_e32 v114, 0
	v_mov_b32_e32 v115, 0
	v_mov_b32_e32 v116, 0
	v_mov_b32_e32 v117, 0
	v_mov_b32_e32 v118, 0
	v_mov_b32_e32 v119, 0
	v_mov_b32_e32 v120, 0
	v_mov_b32_e32 v121, 0
	v_mov_b32_e32 v122, 0
	v_mov_b32_e32 v123, 0
	v_mov_b32_e32 v124, 0
	v_mov_b32_e32 v125, 0
	v_mov_b32_e32 v126, 0
	v_mov_b32_e32 v127, 0
	v_readfirstlane_b32 s61, v143
	v_lshl_add_u64 v[6:7], v[0:1], 0, s[10:11]
	s_mov_b32 m0, s61
	v_readfirstlane_b32 s61, v144
	global_load_lds_dwordx4 v[6:7], off
	v_lshl_add_u64 v[0:1], v[0:1], 0, s[12:13]
	s_mov_b32 m0, s61
	v_readfirstlane_b32 s61, v145
	global_load_lds_dwordx4 v[0:1], off
	v_lshl_add_u64 v[0:1], v[2:3], 0, s[10:11]
	s_mov_b32 m0, s61
	v_readfirstlane_b32 s61, v146
	global_load_lds_dwordx4 v[0:1], off
	v_lshl_add_u64 v[0:1], v[2:3], 0, s[12:13]
	s_mov_b32 m0, s61
	v_readfirstlane_b32 s61, v147
	global_load_lds_dwordx4 v[0:1], off
	v_lshl_add_u64 v[0:1], v[4:5], 0, s[10:11]
	s_mov_b32 m0, s61
	v_readfirstlane_b32 s61, v148
	global_load_lds_dwordx4 v[0:1], off
	v_lshl_add_u64 v[0:1], v[4:5], 0, s[12:13]
	s_mov_b32 m0, s61
	s_nop 0
	global_load_lds_dwordx4 v[0:1], off
	s_and_saveexec_b64 s[70:71], s[4:5]
	s_cbranch_execz .LBB0_410
	s_barrier
.LBB0_410:
	s_or_b64 exec, exec, s[70:71]
	s_waitcnt vmcnt(8)
	s_barrier
	s_add_u32 s66, s6, s66
	s_addc_u32 s67, s7, s67
	s_add_u32 s68, s6, s68
	v_mov_b32_e32 v0, 0
	s_addc_u32 s69, s7, s69
	s_mov_b32 s61, -2
	v_mov_b32_e32 v1, v0
	v_mov_b32_e32 v2, v0
	v_mov_b32_e32 v3, v0
	v_mov_b32_e32 v4, v0
	v_mov_b32_e32 v5, v0
	v_mov_b32_e32 v6, v0
	v_mov_b32_e32 v7, v0
	s_waitcnt vmcnt(6)
	s_sub_u32 s98, s66, 0x100
	s_subb_u32 s99, s67, 0
	v_lshl_add_u64 v[226:227], s[98:99], 0, v[132:133]
	s_barrier

; #define STAGE(P, BASE, br, kt) do { const char* _gb = (const char*)(BASE) + ((size_t)(br) * K + (size_t)(kt) * BK) * 2; \
;     __builtin_amdgcn_global_load_lds((const unsigned*)(_gb + loff0), (unsigned*)((char*)(P) + tid * 16), 16, 0, 0); \
;     __builtin_amdgcn_global_load_lds((const unsigned*)(_gb + (size_t)K * 128 + loff0), (unsigned*)((char*)(P) + tid * 16 + 8192), 16, 0, 0); } while (0)
; #define WAIT_V(n) asm volatile("s_waitcnt vmcnt(" #n ")" ::: "memory")
; #define BAR __builtin_amdgcn_s_barrier()
; template <int EPI> ...
;     ...
;   f32x4 acc[2][2][4][2] = {};
;   bf16x8 At[4][2], B0[2][2], B1[2][2];
;   int nt = K / BK;
;   const int aoff0 = lds_byte(wr * 64 + fr, fq * 8), aoff1 = lds_byte(wr * 64 + fr, 32 + fq * 8);
;   const int brw = wc * 32 + (fr >> 2) * 8 + (fr & 3);
;   const int boff0 = lds_byte(brw, fq * 8), boff1 = lds_byte(brw, 32 + fq * 8);
;   unsigned loff0;
;   { int _r, _c; stage_rc(tid * 16, _r, _c); loff0 = (unsigned)(_r * K + _c) * 2u; }
;   STAGE(SB(0, 0), Bt, bcol, 0); STAGE(SA(0, 0), A, brow, 0);
;   STAGE(SB(0, 1), Bt, bcol + HALF, 0); STAGE(SA(0, 1), A, brow + HALF, 0);
;   if (wr == 1) BAR;
;   WAIT_V(4); BAR;
;   STAGE(SB(1, 0), Bt, bcol, 1); STAGE(SA(1, 0), A, brow, 1); STAGE(SB(1, 1), Bt, bcol + HALF, 1);
;   WAIT_V(6); BAR;
; template <int EPI>
; __device__ __forceinline__ void gemm_phase(const u16* A, const u16* Bt, int M, int N, int K, u16* out, int ldo,
;                                            const float* aux, int bid, int nblk, int wv) {
;     ...
;   for (int base = 0; base < ntile; base += nblk) {
;     int wgid;
;     if (base + nblk <= ntile && (nblk & 7) == 0) wgid = base + (bid & 7) * (nblk >> 3) + (bid >> 3);
;     else wgid = base + bid;
;     if (wgid >= ntile) break;
;     int nig = WGM * nN, gid = wgid / nig, fm = gid * WGM, gsz = min(nM - fm, WGM);
;     int pm = fm + ((wgid % nig) % gsz), pn = (wgid % nig) / gsz;
;     int brow = pm * BM, bcol = pn * BM;
;     gemm_tile<EPI>(A, Bt, K, brow, bcol, out, ldo, EPI == 1 ? pn * HALF : bcol, aux, tid);
.LBB0_1014:
	s_mov_b32 s60, s74
	s_add_i32 s74, s74, s33
	s_cmpk_lt_i32 s74, 0x401
	s_cselect_b64 s[58:59], -1, 0
	s_and_b64 s[58:59], s[44:45], s[58:59]
	s_and_b64 s[58:59], s[58:59], exec
	s_cselect_b32 s58, s86, s91
	s_add_i32 s60, s58, s60
	s_cmpk_gt_i32 s60, 0x3ff
	s_mov_b64 s[58:59], -1
	s_cbranch_scc1 .LBB0_1013
	s_sub_i32 s60, 0x3ff, s60
	s_ashr_i32 s58, s60, 31
	s_lshr_b32 s58, s58, 26
	s_add_i32 s58, s60, s58
	s_and_b32 s59, s58, 0xffc0
	s_sub_i32 s59, s60, s59
	s_bfe_i32 s60, s59, 0x80000
	s_bfe_u32 s60, s60, 0x3000c
	s_add_i32 s60, s59, s60
	s_bfe_i32 s61, s60, 0x80000
	s_and_b32 s60, s60, 0xf8
	s_sub_i32 s59, s59, s60
	s_sext_i32_i8 s59, s59
	s_lshl_b32 s58, s58, 5
	s_sext_i32_i16 s61, s61
	s_and_b32 s58, s58, 0xfffff800
	s_lshl_b32 s59, s59, 8
	s_add_i32 s58, s59, s58
	s_lshl_b32 s59, s61, 5
	s_and_b32 s60, s59, 0xffffff00
	s_ashr_i32 s61, s60, 31
	s_lshl_b64 s[64:65], s[60:61], 12
	s_add_u32 s62, s70, s64
	s_addc_u32 s63, s71, s65
	v_readfirstlane_b32 s59, v135
	v_lshl_add_u64 v[0:1], s[62:63], 0, v[128:129]
	s_mov_b32 m0, s59
	v_readfirstlane_b32 s59, v136
	global_load_lds_dwordx4 v[0:1], off
	s_mov_b32 m0, s59
	s_ashr_i32 s59, s58, 31
	s_lshl_b64 s[66:67], s[58:59], 12
	s_add_u32 s62, s14, s66
	v_lshl_add_u64 v[2:3], v[0:1], 0, s[8:9]
	s_addc_u32 s63, s43, s67
	global_load_lds_dwordx4 v[2:3], off
	v_lshl_add_u64 v[2:3], s[62:63], 0, v[128:129]
	s_or_b32 s62, s60, 0x80
	s_ashr_i32 s63, s62, 31
	v_readfirstlane_b32 s59, v137
	s_lshl_b64 s[62:63], s[62:63], 12
	s_mov_b32 m0, s59
	v_readfirstlane_b32 s59, v138
	s_add_u32 s62, s70, s62
	global_load_lds_dwordx4 v[2:3], off
	v_lshl_add_u64 v[4:5], v[2:3], 0, s[8:9]
	s_mov_b32 m0, s59
	s_addc_u32 s63, s71, s63
	global_load_lds_dwordx4 v[4:5], off
	v_lshl_add_u64 v[4:5], s[62:63], 0, v[128:129]
	s_or_b32 s62, s58, 0x80
	s_ashr_i32 s63, s62, 31
	v_readfirstlane_b32 s59, v139
	s_lshl_b64 s[62:63], s[62:63], 12
	s_mov_b32 m0, s59
	v_readfirstlane_b32 s59, v140
	s_add_u32 s68, s14, s62
	global_load_lds_dwordx4 v[4:5], off
	v_lshl_add_u64 v[6:7], v[4:5], 0, s[8:9]
	s_mov_b32 m0, s59
	s_addc_u32 s69, s43, s63
	v_readfirstlane_b32 s59, v141
	global_load_lds_dwordx4 v[6:7], off
	v_lshl_add_u64 v[6:7], s[68:69], 0, v[128:129]
	s_mov_b32 m0, s59
	v_readfirstlane_b32 s59, v142
	global_load_lds_dwordx4 v[6:7], off
	v_lshl_add_u64 v[6:7], v[6:7], 0, s[8:9]
	s_mov_b32 m0, s59
	s_nop 0
	global_load_lds_dwordx4 v[6:7], off
	v_mov_b32_e32 v8, 0
	v_mov_b32_e32 v9, 0
	v_mov_b32_e32 v10, 0
	v_mov_b32_e32 v11, 0
	v_mov_b32_e32 v12, 0
	v_mov_b32_e32 v13, 0
	v_mov_b32_e32 v14, 0
	v_mov_b32_e32 v15, 0
	v_mov_b32_e32 v16, 0
	v_mov_b32_e32 v17, 0
	v_mov_b32_e32 v18, 0
	v_mov_b32_e32 v19, 0
	v_mov_b32_e32 v20, 0
	v_mov_b32_e32 v21, 0
	v_mov_b32_e32 v22, 0
	v_mov_b32_e32 v23, 0
	v_mov_b32_e32 v24, 0
	v_mov_b32_e32 v25, 0
	v_mov_b32_e32 v26, 0
	v_mov_b32_e32 v27, 0
	v_mov_b32_e32 v28, 0
	v_mov_b32_e32 v29, 0
	v_mov_b32_e32 v30, 0
	v_mov_b32_e32 v31, 0
	v_mov_b32_e32 v32, 0
	v_mov_b32_e32 v33, 0
	v_mov_b32_e32 v34, 0
	v_mov_b32_e32 v35, 0
	v_mov_b32_e32 v36, 0
	v_mov_b32_e32 v37, 0
	v_mov_b32_e32 v38, 0
	v_mov_b32_e32 v39, 0
	v_mov_b32_e32 v40, 0
	v_mov_b32_e32 v41, 0
	v_mov_b32_e32 v42, 0
	v_mov_b32_e32 v43, 0
	v_mov_b32_e32 v44, 0
	v_mov_b32_e32 v45, 0
	v_mov_b32_e32 v46, 0
	v_mov_b32_e32 v47, 0
	v_mov_b32_e32 v48, 0
	v_mov_b32_e32 v49, 0
	v_mov_b32_e32 v50, 0
	v_mov_b32_e32 v51, 0
	v_mov_b32_e32 v52, 0
	v_mov_b32_e32 v53, 0
	v_mov_b32_e32 v54, 0
	v_mov_b32_e32 v55, 0
	v_mov_b32_e32 v56, 0
	v_mov_b32_e32 v57, 0
	v_mov_b32_e32 v58, 0
	v_mov_b32_e32 v59, 0
	v_mov_b32_e32 v60, 0
	v_mov_b32_e32 v61, 0
	v_mov_b32_e32 v62, 0
	v_mov_b32_e32 v63, 0
	v_mov_b32_e32 v64, 0
	v_mov_b32_e32 v65, 0
	v_mov_b32_e32 v66, 0
	v_mov_b32_e32 v67, 0
	v_mov_b32_e32 v68, 0
	v_mov_b32_e32 v69, 0
	v_mov_b32_e32 v70, 0
	v_mov_b32_e32 v71, 0
	v_mov_b32_e32 v72, 0
	v_mov_b32_e32 v73, 0
	v_mov_b32_e32 v74, 0
	v_mov_b32_e32 v75, 0
	v_mov_b32_e32 v76, 0
	v_mov_b32_e32 v77, 0
	v_mov_b32_e32 v78, 0
	v_mov_b32_e32 v79, 0
	v_mov_b32_e32 v80, 0
	v_mov_b32_e32 v81, 0
	v_mov_b32_e32 v82, 0
	v_mov_b32_e32 v83, 0
	v_mov_b32_e32 v84, 0
	v_mov_b32_e32 v85, 0
	v_mov_b32_e32 v86, 0
	v_mov_b32_e32 v87, 0
	v_mov_b32_e32 v88, 0
	v_mov_b32_e32 v89, 0
	v_mov_b32_e32 v90, 0
	v_mov_b32_e32 v91, 0
	v_mov_b32_e32 v92, 0
	v_mov_b32_e32 v93, 0
	v_mov_b32_e32 v94, 0
	v_mov_b32_e32 v95, 0
	v_mov_b32_e32 v96, 0
	v_mov_b32_e32 v97, 0
	v_mov_b32_e32 v98, 0
	v_mov_b32_e32 v99, 0
	v_mov_b32_e32 v100, 0
	v_mov_b32_e32 v101, 0
	v_mov_b32_e32 v102, 0
	v_mov_b32_e32 v103, 0
	v_mov_b32_e32 v104, 0
	v_mov_b32_e32 v105, 0
	v_mov_b32_e32 v106, 0
	v_mov_b32_e32 v107, 0
	v_mov_b32_e32 v108, 0
	v_mov_b32_e32 v109, 0
	v_mov_b32_e32 v110, 0
	v_mov_b32_e32 v111, 0
	v_mov_b32_e32 v112, 0
	v_mov_b32_e32 v113, 0
	v_mov_b32_e32 v114, 0
	v_mov_b32_e32 v115, 0
	v_mov_b32_e32 v116, 0
	v_mov_b32_e32 v117, 0
	v_mov_b32_e32 v118, 0
	v_mov_b32_e32 v119, 0
	v_mov_b32_e32 v120, 0
	v_mov_b32_e32 v121, 0
	v_mov_b32_e32 v122, 0
	v_mov_b32_e32 v123, 0
	v_mov_b32_e32 v124, 0
	v_mov_b32_e32 v125, 0
	v_mov_b32_e32 v126, 0
	v_mov_b32_e32 v127, 0
	v_readfirstlane_b32 s59, v143
	v_lshl_add_u64 v[6:7], v[0:1], 0, s[10:11]
	s_mov_b32 m0, s59
	v_readfirstlane_b32 s59, v144
	global_load_lds_dwordx4 v[6:7], off
	v_lshl_add_u64 v[0:1], v[0:1], 0, s[12:13]
	s_mov_b32 m0, s59
	v_readfirstlane_b32 s59, v145
	global_load_lds_dwordx4 v[0:1], off
	v_lshl_add_u64 v[0:1], v[2:3], 0, s[10:11]
	s_mov_b32 m0, s59
	v_readfirstlane_b32 s59, v146
	global_load_lds_dwordx4 v[0:1], off
	v_lshl_add_u64 v[0:1], v[2:3], 0, s[12:13]
	s_mov_b32 m0, s59
	v_readfirstlane_b32 s59, v147
	global_load_lds_dwordx4 v[0:1], off
	v_lshl_add_u64 v[0:1], v[4:5], 0, s[10:11]
	s_mov_b32 m0, s59
	v_readfirstlane_b32 s59, v148
	global_load_lds_dwordx4 v[0:1], off
	v_lshl_add_u64 v[0:1], v[4:5], 0, s[12:13]
	s_mov_b32 m0, s59
	s_nop 0
	global_load_lds_dwordx4 v[0:1], off
	s_and_saveexec_b64 s[68:69], s[4:5]
	s_cbranch_execz .LBB0_1017
	s_barrier
.LBB0_1017:
	s_or_b64 exec, exec, s[68:69]
	s_waitcnt vmcnt(8)
	s_barrier
	s_add_u32 s64, s6, s64
	s_addc_u32 s65, s7, s65
	s_add_u32 s66, s6, s66
	v_mov_b32_e32 v0, 0
	s_addc_u32 s67, s7, s67
	s_mov_b32 s59, -2
	v_mov_b32_e32 v1, v0
	v_mov_b32_e32 v2, v0
	v_mov_b32_e32 v3, v0
	v_mov_b32_e32 v4, v0
	v_mov_b32_e32 v5, v0
	v_mov_b32_e32 v6, v0
	v_mov_b32_e32 v7, v0
	s_waitcnt vmcnt(6)
	s_sub_u32 s98, s64, 0x100
	s_subb_u32 s99, s65, 0
	v_lshl_add_u64 v[226:227], s[98:99], 0, v[132:133]
	s_barrier

; #define STAGE(P, BASE, br, kt) do { const char* _gb = (const char*)(BASE) + ((size_t)(br) * K + (size_t)(kt) * BK) * 2; \
;     __builtin_amdgcn_global_load_lds((const unsigned*)(_gb + loff0), (unsigned*)((char*)(P) + tid * 16), 16, 0, 0); \
;     __builtin_amdgcn_global_load_lds((const unsigned*)(_gb + (size_t)K * 128 + loff0), (unsigned*)((char*)(P) + tid * 16 + 8192), 16, 0, 0); } while (0)
; #define WAIT_V(n) asm volatile("s_waitcnt vmcnt(" #n ")" ::: "memory")
; #define BAR __builtin_amdgcn_s_barrier()
; template <int EPI> ...
;     ...
;   f32x4 acc[2][2][4][2] = {};
;   bf16x8 At[4][2], B0[2][2], B1[2][2];
;   int nt = K / BK;
;   const int aoff0 = lds_byte(wr * 64 + fr, fq * 8), aoff1 = lds_byte(wr * 64 + fr, 32 + fq * 8);
;   const int brw = wc * 32 + (fr >> 2) * 8 + (fr & 3);
;   const int boff0 = lds_byte(brw, fq * 8), boff1 = lds_byte(brw, 32 + fq * 8);
;   unsigned loff0;
;   { int _r, _c; stage_rc(tid * 16, _r, _c); loff0 = (unsigned)(_r * K + _c) * 2u; }
;   STAGE(SB(0, 0), Bt, bcol, 0); STAGE(SA(0, 0), A, brow, 0);
;   STAGE(SB(0, 1), Bt, bcol + HALF, 0); STAGE(SA(0, 1), A, brow + HALF, 0);
;   if (wr == 1) BAR;
;   WAIT_V(4); BAR;
;   STAGE(SB(1, 0), Bt, bcol, 1); STAGE(SA(1, 0), A, brow, 1); STAGE(SB(1, 1), Bt, bcol + HALF, 1);
;   WAIT_V(6); BAR;
; template <int EPI>
; __device__ __forceinline__ void gemm_phase(const u16* A, const u16* Bt, int M, int N, int K, u16* out, int ldo,
;                                            const float* aux, int bid, int nblk, int wv) {
;     ...
;   for (int base = 0; base < ntile; base += nblk) {
;     int wgid;
;     if (base + nblk <= ntile && (nblk & 7) == 0) wgid = base + (bid & 7) * (nblk >> 3) + (bid >> 3);
;     else wgid = base + bid;
;     if (wgid >= ntile) break;
;     int nig = WGM * nN, gid = wgid / nig, fm = gid * WGM, gsz = min(nM - fm, WGM);
;     int pm = fm + ((wgid % nig) % gsz), pn = (wgid % nig) / gsz;
;     int brow = pm * BM, bcol = pn * BM;
;     gemm_tile<EPI>(A, Bt, K, brow, bcol, out, ldo, EPI == 1 ? pn * HALF : bcol, aux, tid);
.LBB0_1101:
	s_mov_b32 s66, s74
	s_add_i32 s74, s74, s33
	s_cmpk_lt_i32 s74, 0x1601
	s_cselect_b64 s[64:65], -1, 0
	s_and_b64 s[64:65], s[44:45], s[64:65]
	s_and_b64 s[64:65], s[64:65], exec
	s_cselect_b32 s64, s86, s91
	s_add_i32 s66, s64, s66
	s_cmpk_gt_i32 s66, 0x15ff
	s_mov_b64 s[64:65], -1
	s_cbranch_scc1 .LBB0_1100
	s_mul_hi_i32 s64, s66, 0x2e8ba2e9
	s_lshr_b32 s65, s64, 31
	s_ashr_i32 s64, s64, 6
	s_add_i32 s64, s64, s65
	s_mul_i32 s65, s64, 0x160
	s_sub_i32 s65, s66, s65
	s_sext_i32_i16 s66, s65
	s_bfe_u32 s66, s66, 0x3001c
	s_add_i32 s66, s65, s66
	s_sext_i32_i16 s67, s66
	s_and_b32 s66, s66, 0xfff8
	s_sub_i32 s65, s65, s66
	s_ashr_i32 s76, s67, 3
	s_sext_i32_i16 s65, s65
	s_lshl_b32 s70, s76, 8
	s_lshl_b32 s64, s64, 11
	s_lshl_b32 s65, s65, 8
	s_ashr_i32 s71, s70, 31
	s_add_i32 s64, s65, s64
	s_lshl_b64 s[68:69], s[70:71], 12
	s_add_u32 s66, s72, s68
	s_addc_u32 s67, s73, s69
	v_readfirstlane_b32 s65, v136
	v_lshl_add_u64 v[0:1], s[66:67], 0, v[128:129]
	s_mov_b32 m0, s65
	v_readfirstlane_b32 s65, v137
	global_load_lds_dwordx4 v[0:1], off
	s_mov_b32 m0, s65
	s_ashr_i32 s65, s64, 31
	s_lshl_b64 s[66:67], s[64:65], 12
	s_add_u32 s78, s14, s66
	s_addc_u32 s79, s43, s67
	s_bitset1_b32 s70, 7
	s_ashr_i32 s71, s70, 31
	v_lshl_add_u64 v[2:3], v[0:1], 0, s[10:11]
	v_readfirstlane_b32 s65, v138
	s_lshl_b64 s[70:71], s[70:71], 12
	global_load_lds_dwordx4 v[2:3], off
	v_lshl_add_u64 v[2:3], s[78:79], 0, v[128:129]
	s_mov_b32 m0, s65
	v_readfirstlane_b32 s65, v139
	s_add_u32 s70, s72, s70
	global_load_lds_dwordx4 v[2:3], off
	v_lshl_add_u64 v[4:5], v[2:3], 0, s[10:11]
	s_mov_b32 m0, s65
	s_addc_u32 s71, s73, s71
	global_load_lds_dwordx4 v[4:5], off
	v_lshl_add_u64 v[4:5], s[70:71], 0, v[128:129]
	s_or_b32 s70, s64, 0x80
	s_ashr_i32 s71, s70, 31
	v_readfirstlane_b32 s65, v140
	s_lshl_b64 s[70:71], s[70:71], 12
	s_mov_b32 m0, s65
	v_readfirstlane_b32 s65, v141
	s_add_u32 s70, s14, s70
	global_load_lds_dwordx4 v[4:5], off
	v_lshl_add_u64 v[6:7], v[4:5], 0, s[10:11]
	s_mov_b32 m0, s65
	s_addc_u32 s71, s43, s71
	v_readfirstlane_b32 s65, v142
	global_load_lds_dwordx4 v[6:7], off
	v_lshl_add_u64 v[132:133], s[70:71], 0, v[128:129]
	s_mov_b32 m0, s65
	v_readfirstlane_b32 s65, v143
	global_load_lds_dwordx4 v[132:133], off
	v_lshl_add_u64 v[6:7], v[132:133], 0, s[10:11]
	s_mov_b32 m0, s65
	s_nop 0
	global_load_lds_dwordx4 v[6:7], off
	v_mov_b32_e32 v8, 0
	v_mov_b32_e32 v9, 0
	v_mov_b32_e32 v10, 0
	v_mov_b32_e32 v11, 0
	v_mov_b32_e32 v12, 0
	v_mov_b32_e32 v13, 0
	v_mov_b32_e32 v14, 0
	v_mov_b32_e32 v15, 0
	v_mov_b32_e32 v16, 0
	v_mov_b32_e32 v17, 0
	v_mov_b32_e32 v18, 0
	v_mov_b32_e32 v19, 0
	v_mov_b32_e32 v20, 0
	v_mov_b32_e32 v21, 0
	v_mov_b32_e32 v22, 0
	v_mov_b32_e32 v23, 0
	v_mov_b32_e32 v24, 0
	v_mov_b32_e32 v25, 0
	v_mov_b32_e32 v26, 0
	v_mov_b32_e32 v27, 0
	v_mov_b32_e32 v28, 0
	v_mov_b32_e32 v29, 0
	v_mov_b32_e32 v30, 0
	v_mov_b32_e32 v31, 0
	v_mov_b32_e32 v32, 0
	v_mov_b32_e32 v33, 0
	v_mov_b32_e32 v34, 0
	v_mov_b32_e32 v35, 0
	v_mov_b32_e32 v36, 0
	v_mov_b32_e32 v37, 0
	v_mov_b32_e32 v38, 0
	v_mov_b32_e32 v39, 0
	v_mov_b32_e32 v40, 0
	v_mov_b32_e32 v41, 0
	v_mov_b32_e32 v42, 0
	v_mov_b32_e32 v43, 0
	v_mov_b32_e32 v44, 0
	v_mov_b32_e32 v45, 0
	v_mov_b32_e32 v46, 0
	v_mov_b32_e32 v47, 0
	v_mov_b32_e32 v48, 0
	v_mov_b32_e32 v49, 0
	v_mov_b32_e32 v50, 0
	v_mov_b32_e32 v51, 0
	v_mov_b32_e32 v52, 0
	v_mov_b32_e32 v53, 0
	v_mov_b32_e32 v54, 0
	v_mov_b32_e32 v55, 0
	v_mov_b32_e32 v56, 0
	v_mov_b32_e32 v57, 0
	v_mov_b32_e32 v58, 0
	v_mov_b32_e32 v59, 0
	v_mov_b32_e32 v60, 0
	v_mov_b32_e32 v61, 0
	v_mov_b32_e32 v62, 0
	v_mov_b32_e32 v63, 0
	v_mov_b32_e32 v64, 0
	v_mov_b32_e32 v65, 0
	v_mov_b32_e32 v66, 0
	v_mov_b32_e32 v67, 0
	v_mov_b32_e32 v68, 0
	v_mov_b32_e32 v69, 0
	v_mov_b32_e32 v70, 0
	v_mov_b32_e32 v71, 0
	v_mov_b32_e32 v72, 0
	v_mov_b32_e32 v73, 0
	v_mov_b32_e32 v74, 0
	v_mov_b32_e32 v75, 0
	v_mov_b32_e32 v76, 0
	v_mov_b32_e32 v77, 0
	v_mov_b32_e32 v78, 0
	v_mov_b32_e32 v79, 0
	v_mov_b32_e32 v80, 0
	v_mov_b32_e32 v81, 0
	v_mov_b32_e32 v82, 0
	v_mov_b32_e32 v83, 0
	v_mov_b32_e32 v84, 0
	v_mov_b32_e32 v85, 0
	v_mov_b32_e32 v86, 0
	v_mov_b32_e32 v87, 0
	v_mov_b32_e32 v88, 0
	v_mov_b32_e32 v89, 0
	v_mov_b32_e32 v90, 0
	v_mov_b32_e32 v91, 0
	v_mov_b32_e32 v92, 0
	v_mov_b32_e32 v93, 0
	v_mov_b32_e32 v94, 0
	v_mov_b32_e32 v95, 0
	v_mov_b32_e32 v96, 0
	v_mov_b32_e32 v97, 0
	v_mov_b32_e32 v98, 0
	v_mov_b32_e32 v99, 0
	v_mov_b32_e32 v100, 0
	v_mov_b32_e32 v101, 0
	v_mov_b32_e32 v102, 0
	v_mov_b32_e32 v103, 0
	v_mov_b32_e32 v104, 0
	v_mov_b32_e32 v105, 0
	v_mov_b32_e32 v106, 0
	v_mov_b32_e32 v107, 0
	v_mov_b32_e32 v108, 0
	v_mov_b32_e32 v109, 0
	v_mov_b32_e32 v110, 0
	v_mov_b32_e32 v111, 0
	v_mov_b32_e32 v112, 0
	v_mov_b32_e32 v113, 0
	v_mov_b32_e32 v114, 0
	v_mov_b32_e32 v115, 0
	v_mov_b32_e32 v116, 0
	v_mov_b32_e32 v117, 0
	v_mov_b32_e32 v118, 0
	v_mov_b32_e32 v119, 0
	v_mov_b32_e32 v120, 0
	v_mov_b32_e32 v121, 0
	v_mov_b32_e32 v122, 0
	v_mov_b32_e32 v123, 0
	v_mov_b32_e32 v124, 0
	v_mov_b32_e32 v125, 0
	v_mov_b32_e32 v126, 0
	v_mov_b32_e32 v127, 0
	v_readfirstlane_b32 s65, v144
	v_lshl_add_u64 v[6:7], v[0:1], 0, s[12:13]
	s_mov_b32 m0, s65
	v_readfirstlane_b32 s65, v145
	global_load_lds_dwordx4 v[6:7], off
	v_lshl_add_u64 v[0:1], v[0:1], 0, s[16:17]
	s_mov_b32 m0, s65
	v_readfirstlane_b32 s65, v146
	global_load_lds_dwordx4 v[0:1], off
	v_lshl_add_u64 v[0:1], v[2:3], 0, s[12:13]
	s_mov_b32 m0, s65
	v_readfirstlane_b32 s65, v147
	global_load_lds_dwordx4 v[0:1], off
	v_lshl_add_u64 v[0:1], v[2:3], 0, s[16:17]
	s_mov_b32 m0, s65
	v_readfirstlane_b32 s65, v148
	global_load_lds_dwordx4 v[0:1], off
	v_lshl_add_u64 v[0:1], v[4:5], 0, s[12:13]
	s_mov_b32 m0, s65
	v_readfirstlane_b32 s65, v149
	global_load_lds_dwordx4 v[0:1], off
	v_lshl_add_u64 v[0:1], v[4:5], 0, s[16:17]
	s_mov_b32 m0, s65
	s_nop 0
	global_load_lds_dwordx4 v[0:1], off
	s_and_saveexec_b64 s[70:71], s[4:5]
	s_cbranch_execz .LBB0_1104
	s_barrier
.LBB0_1104:
	s_or_b64 exec, exec, s[70:71]
	s_waitcnt vmcnt(8)
	s_barrier
	s_add_u32 s66, s6, s66
	s_addc_u32 s67, s7, s67
	s_add_u32 s68, s6, s68
	v_mov_b32_e32 v0, 0
	s_addc_u32 s69, s7, s69
	s_mov_b32 s65, -2
	v_mov_b32_e32 v1, v0
	v_mov_b32_e32 v2, v0
	v_mov_b32_e32 v3, v0
	v_mov_b32_e32 v4, v0
	v_mov_b32_e32 v5, v0
	v_mov_b32_e32 v6, v0
	v_mov_b32_e32 v7, v0
	s_waitcnt vmcnt(6)
	s_sub_u32 s98, s68, 0x100
	s_subb_u32 s99, s69, 0
	v_lshl_add_u64 v[228:229], s[98:99], 0, v[130:131]
	s_barrier

; #define STAGE(P, BASE, br, kt) do { const char* _gb = (const char*)(BASE) + ((size_t)(br) * K + (size_t)(kt) * BK) * 2; \
;     __builtin_amdgcn_global_load_lds((const unsigned*)(_gb + loff0), (unsigned*)((char*)(P) + tid * 16), 16, 0, 0); \
;     __builtin_amdgcn_global_load_lds((const unsigned*)(_gb + (size_t)K * 128 + loff0), (unsigned*)((char*)(P) + tid * 16 + 8192), 16, 0, 0); } while (0)
; #define WAIT_V(n) asm volatile("s_waitcnt vmcnt(" #n ")" ::: "memory")
; #define BAR __builtin_amdgcn_s_barrier()
; template <int EPI> ...
;     ...
;   f32x4 acc[2][2][4][2] = {};
;   bf16x8 At[4][2], B0[2][2], B1[2][2];
;   int nt = K / BK;
;   const int aoff0 = lds_byte(wr * 64 + fr, fq * 8), aoff1 = lds_byte(wr * 64 + fr, 32 + fq * 8);
;   const int brw = wc * 32 + (fr >> 2) * 8 + (fr & 3);
;   const int boff0 = lds_byte(brw, fq * 8), boff1 = lds_byte(brw, 32 + fq * 8);
;   unsigned loff0;
;   { int _r, _c; stage_rc(tid * 16, _r, _c); loff0 = (unsigned)(_r * K + _c) * 2u; }
;   STAGE(SB(0, 0), Bt, bcol, 0); STAGE(SA(0, 0), A, brow, 0);
;   STAGE(SB(0, 1), Bt, bcol + HALF, 0); STAGE(SA(0, 1), A, brow + HALF, 0);
;   if (wr == 1) BAR;
;   WAIT_V(4); BAR;
;   STAGE(SB(1, 0), Bt, bcol, 1); STAGE(SA(1, 0), A, brow, 1); STAGE(SB(1, 1), Bt, bcol + HALF, 1);
;   WAIT_V(6); BAR;
; template <int EPI>
; __device__ __forceinline__ void gemm_phase(const u16* A, const u16* Bt, int M, int N, int K, u16* out, int ldo,
;                                            const float* aux, int bid, int nblk, int wv) {
;     ...
;   for (int base = 0; base < ntile; base += nblk) {
;     int wgid;
;     if (base + nblk <= ntile && (nblk & 7) == 0) wgid = base + (bid & 7) * (nblk >> 3) + (bid >> 3);
;     else wgid = base + bid;
;     if (wgid >= ntile) break;
;     int nig = WGM * nN, gid = wgid / nig, fm = gid * WGM, gsz = min(nM - fm, WGM);
;     int pm = fm + ((wgid % nig) % gsz), pn = (wgid % nig) / gsz;
;     int brow = pm * BM, bcol = pn * BM;
;     gemm_tile<EPI>(A, Bt, K, brow, bcol, out, ldo, EPI == 1 ? pn * HALF : bcol, aux, tid);
.LBB0_1148:
	s_mov_b32 s60, s70
	s_add_i32 s70, s70, s33
	s_cmpk_lt_i32 s70, 0x401
	s_cselect_b64 s[58:59], -1, 0
	s_and_b64 s[58:59], s[44:45], s[58:59]
	s_and_b64 s[58:59], s[58:59], exec
	s_cselect_b32 s58, s86, s91
	s_add_i32 s60, s58, s60
	s_cmpk_gt_i32 s60, 0x3ff
	s_mov_b64 s[58:59], -1
	s_cbranch_scc1 .LBB0_1147
	s_sub_i32 s60, 0x3ff, s60
	s_ashr_i32 s58, s60, 31
	s_lshr_b32 s58, s58, 26
	s_add_i32 s58, s60, s58
	s_and_b32 s59, s58, 0xffc0
	s_sub_i32 s59, s60, s59
	s_bfe_i32 s60, s59, 0x80000
	s_bfe_u32 s60, s60, 0x3000c
	s_add_i32 s60, s59, s60
	s_bfe_i32 s61, s60, 0x80000
	s_and_b32 s60, s60, 0xf8
	s_sub_i32 s59, s59, s60
	s_sext_i32_i16 s61, s61
	s_sext_i32_i8 s59, s59
	s_lshl_b32 s58, s58, 5
	s_ashr_i32 s62, s61, 3
	s_and_b32 s58, s58, 0xfffff800
	s_lshl_b32 s71, s59, 8
	s_add_i32 s71, s71, s58
	s_lshl_b32 s58, s62, 8
	s_mul_i32 s64, s62, 0x2c0000
	s_mul_hi_i32 s65, s58, 0x2c00
	s_add_u32 s60, s66, s64
	s_addc_u32 s61, s67, s65
	v_readfirstlane_b32 s59, v135
	s_mul_i32 s75, s71, 0x2c00
	v_lshl_add_u64 v[0:1], s[60:61], 0, v[128:129]
	s_mov_b32 m0, s59
	v_readfirstlane_b32 s59, v136
	s_mul_hi_i32 s74, s71, 0x2c00
	s_add_u32 s60, s14, s75
	global_load_lds_dwordx4 v[0:1], off
	v_lshl_add_u64 v[2:3], v[0:1], 0, s[8:9]
	s_mov_b32 m0, s59
	s_addc_u32 s61, s43, s74
	global_load_lds_dwordx4 v[2:3], off
	v_lshl_add_u64 v[2:3], s[60:61], 0, v[128:129]
	s_mul_i32 s60, s62, 0x160000
	v_readfirstlane_b32 s59, v137
	s_ashr_i32 s61, s60, 31
	s_mov_b32 m0, s59
	v_readfirstlane_b32 s59, v138
	s_lshl_b64 s[60:61], s[60:61], 1
	global_load_lds_dwordx4 v[2:3], off
	s_mov_b32 m0, s59
	s_add_u32 s59, s66, s60
	s_addc_u32 s63, s67, s61
	s_add_u32 s62, s59, 0x160000
	v_lshl_add_u64 v[4:5], v[2:3], 0, s[8:9]
	s_addc_u32 s63, s63, 0
	v_readfirstlane_b32 s59, v139
	global_load_lds_dwordx4 v[4:5], off
	v_lshl_add_u64 v[4:5], s[62:63], 0, v[128:129]
	s_mov_b32 m0, s59
	v_readfirstlane_b32 s59, v140
	global_load_lds_dwordx4 v[4:5], off
	s_mov_b32 m0, s59
	s_or_b32 s59, s71, 0x80
	s_mul_i32 s73, s59, 0x2c00
	s_mul_hi_i32 s72, s59, 0x2c00
	s_add_u32 s62, s14, s73
	v_lshl_add_u64 v[6:7], v[4:5], 0, s[8:9]
	s_addc_u32 s63, s43, s72
	v_readfirstlane_b32 s59, v141
	global_load_lds_dwordx4 v[6:7], off
	v_lshl_add_u64 v[6:7], s[62:63], 0, v[128:129]
	s_mov_b32 m0, s59
	v_readfirstlane_b32 s59, v142
	global_load_lds_dwordx4 v[6:7], off
	v_lshl_add_u64 v[6:7], v[6:7], 0, s[8:9]
	s_mov_b32 m0, s59
	s_nop 0
	global_load_lds_dwordx4 v[6:7], off
	v_mov_b32_e32 v8, 0
	v_mov_b32_e32 v9, 0
	v_mov_b32_e32 v10, 0
	v_mov_b32_e32 v11, 0
	v_mov_b32_e32 v12, 0
	v_mov_b32_e32 v13, 0
	v_mov_b32_e32 v14, 0
	v_mov_b32_e32 v15, 0
	v_mov_b32_e32 v16, 0
	v_mov_b32_e32 v17, 0
	v_mov_b32_e32 v18, 0
	v_mov_b32_e32 v19, 0
	v_mov_b32_e32 v20, 0
	v_mov_b32_e32 v21, 0
	v_mov_b32_e32 v22, 0
	v_mov_b32_e32 v23, 0
	v_mov_b32_e32 v24, 0
	v_mov_b32_e32 v25, 0
	v_mov_b32_e32 v26, 0
	v_mov_b32_e32 v27, 0
	v_mov_b32_e32 v28, 0
	v_mov_b32_e32 v29, 0
	v_mov_b32_e32 v30, 0
	v_mov_b32_e32 v31, 0
	v_mov_b32_e32 v32, 0
	v_mov_b32_e32 v33, 0
	v_mov_b32_e32 v34, 0
	v_mov_b32_e32 v35, 0
	v_mov_b32_e32 v36, 0
	v_mov_b32_e32 v37, 0
	v_mov_b32_e32 v38, 0
	v_mov_b32_e32 v39, 0
	v_mov_b32_e32 v40, 0
	v_mov_b32_e32 v41, 0
	v_mov_b32_e32 v42, 0
	v_mov_b32_e32 v43, 0
	v_mov_b32_e32 v44, 0
	v_mov_b32_e32 v45, 0
	v_mov_b32_e32 v46, 0
	v_mov_b32_e32 v47, 0
	v_mov_b32_e32 v48, 0
	v_mov_b32_e32 v49, 0
	v_mov_b32_e32 v50, 0
	v_mov_b32_e32 v51, 0
	v_mov_b32_e32 v52, 0
	v_mov_b32_e32 v53, 0
	v_mov_b32_e32 v54, 0
	v_mov_b32_e32 v55, 0
	v_mov_b32_e32 v56, 0
	v_mov_b32_e32 v57, 0
	v_mov_b32_e32 v58, 0
	v_mov_b32_e32 v59, 0
	v_mov_b32_e32 v60, 0
	v_mov_b32_e32 v61, 0
	v_mov_b32_e32 v62, 0
	v_mov_b32_e32 v63, 0
	v_mov_b32_e32 v64, 0
	v_mov_b32_e32 v65, 0
	v_mov_b32_e32 v66, 0
	v_mov_b32_e32 v67, 0
	v_mov_b32_e32 v68, 0
	v_mov_b32_e32 v69, 0
	v_mov_b32_e32 v70, 0
	v_mov_b32_e32 v71, 0
	v_mov_b32_e32 v72, 0
	v_mov_b32_e32 v73, 0
	v_mov_b32_e32 v74, 0
	v_mov_b32_e32 v75, 0
	v_mov_b32_e32 v76, 0
	v_mov_b32_e32 v77, 0
	v_mov_b32_e32 v78, 0
	v_mov_b32_e32 v79, 0
	v_mov_b32_e32 v80, 0
	v_mov_b32_e32 v81, 0
	v_mov_b32_e32 v82, 0
	v_mov_b32_e32 v83, 0
	v_mov_b32_e32 v84, 0
	v_mov_b32_e32 v85, 0
	v_mov_b32_e32 v86, 0
	v_mov_b32_e32 v87, 0
	v_mov_b32_e32 v88, 0
	v_mov_b32_e32 v89, 0
	v_mov_b32_e32 v90, 0
	v_mov_b32_e32 v91, 0
	v_mov_b32_e32 v92, 0
	v_mov_b32_e32 v93, 0
	v_mov_b32_e32 v94, 0
	v_mov_b32_e32 v95, 0
	v_mov_b32_e32 v96, 0
	v_mov_b32_e32 v97, 0
	v_mov_b32_e32 v98, 0
	v_mov_b32_e32 v99, 0
	v_mov_b32_e32 v100, 0
	v_mov_b32_e32 v101, 0
	v_mov_b32_e32 v102, 0
	v_mov_b32_e32 v103, 0
	v_mov_b32_e32 v104, 0
	v_mov_b32_e32 v105, 0
	v_mov_b32_e32 v106, 0
	v_mov_b32_e32 v107, 0
	v_mov_b32_e32 v108, 0
	v_mov_b32_e32 v109, 0
	v_mov_b32_e32 v110, 0
	v_mov_b32_e32 v111, 0
	v_mov_b32_e32 v112, 0
	v_mov_b32_e32 v113, 0
	v_mov_b32_e32 v114, 0
	v_mov_b32_e32 v115, 0
	v_mov_b32_e32 v116, 0
	v_mov_b32_e32 v117, 0
	v_mov_b32_e32 v118, 0
	v_mov_b32_e32 v119, 0
	v_mov_b32_e32 v120, 0
	v_mov_b32_e32 v121, 0
	v_mov_b32_e32 v122, 0
	v_mov_b32_e32 v123, 0
	v_mov_b32_e32 v124, 0
	v_mov_b32_e32 v125, 0
	v_mov_b32_e32 v126, 0
	v_mov_b32_e32 v127, 0
	v_readfirstlane_b32 s62, v143
	v_lshl_add_u64 v[6:7], v[0:1], 0, s[10:11]
	s_mov_b32 m0, s62
	v_readfirstlane_b32 s62, v144
	global_load_lds_dwordx4 v[6:7], off
	v_lshl_add_u64 v[0:1], v[0:1], 0, s[12:13]
	s_mov_b32 m0, s62
	v_readfirstlane_b32 s62, v145
	global_load_lds_dwordx4 v[0:1], off
	v_lshl_add_u64 v[0:1], v[2:3], 0, s[10:11]
	s_mov_b32 m0, s62
	v_readfirstlane_b32 s62, v146
	global_load_lds_dwordx4 v[0:1], off
	v_lshl_add_u64 v[0:1], v[2:3], 0, s[12:13]
	s_mov_b32 m0, s62
	v_readfirstlane_b32 s62, v147
	global_load_lds_dwordx4 v[0:1], off
	v_lshl_add_u64 v[0:1], v[4:5], 0, s[10:11]
	s_mov_b32 m0, s62
	v_readfirstlane_b32 s62, v148
	global_load_lds_dwordx4 v[0:1], off
	v_lshl_add_u64 v[0:1], v[4:5], 0, s[12:13]
	s_mov_b32 m0, s62
	s_nop 0
	global_load_lds_dwordx4 v[0:1], off
	s_and_saveexec_b64 s[62:63], s[4:5]
	s_cbranch_execz .LBB0_1151
	s_barrier
.LBB0_1151:
	s_or_b64 exec, exec, s[62:63]
	s_waitcnt vmcnt(8)
	s_barrier
	s_ashr_i32 s59, s58, 31
	s_add_u32 s60, s6, s60
	s_addc_u32 s61, s7, s61
	s_add_u32 s62, s6, s75
	s_addc_u32 s63, s7, s74
	s_add_u32 s64, s6, s64
	v_mov_b32_e32 v0, 0
	s_addc_u32 s65, s7, s65
	s_mov_b32 s74, -2
	v_mov_b32_e32 v1, v0
	v_mov_b32_e32 v2, v0
	v_mov_b32_e32 v3, v0
	v_mov_b32_e32 v4, v0
	v_mov_b32_e32 v5, v0
	v_mov_b32_e32 v6, v0
	v_mov_b32_e32 v7, v0
	s_waitcnt vmcnt(6)
	s_sub_u32 s98, s60, 0x100
	s_subb_u32 s99, s61, 0
	v_lshl_add_u64 v[228:229], s[98:99], 0, v[132:133]
	s_barrier
